# PEER table quantisation moved from the in-proj phase to the start of the layer-0 attention phase (workgroups 0..255 only, CU partner runs attention items meanwhile)
# speedup vs baseline: 1.0017x; 1.0017x over previous
; DEV int opaque_tid() { int t = (int)threadIdx.x; asm volatile("" : "+v"(t)); return t; }
; __device__ void run_phase(const Params& P, int ph, char* smem, bool do_store) {
;     ...
;       if (l == 0 && quant_first) { quant_rows_fp6(P.peer_u, P.U8, P.SU, 2 * 16384); quant_rows_fp4(P.peer_v, P.V8, P.SV, 2 * 16384); }
;     ...
;     case 2: {
;       {
;         unsigned* qh = P.bar + XCD_BAR_WORDS + l * 8 * 64;
;         unsigned* slot = (unsigned*)(smem + 73712);
;         for (int qi = 0; qi < 8; ++qi) {
;           const int qsel = (bid + qi) & 7;
;           for (;;) {
;             __syncthreads();
;             if (opaque_tid() == 0) *slot = __hip_atomic_fetch_add(&qh[qsel * 64], 1u, __ATOMIC_RELAXED, __HIP_MEMORY_SCOPE_AGENT);
;             __syncthreads();
;             const unsigned k = *slot;
;             if (k >= 128u) break;
;             nsa_item(P, l, (int)((127u - k) << 3) | qsel, smem);
;           }
;         }
.LBB0_144:
	s_and_b64 vcc, exec, s[0:1]
	s_cbranch_vccz .LBB0_221
	v_readlane_b32 s0, v248, 3
	v_readlane_b32 s1, v248, 4
	s_nop 0
	s_and_b64 vcc, exec, s[0:1]
	s_cbranch_vccnz .Lq_entry
.Lnsa_resume:
	s_mov_b32 s2, 0
	v_readlane_b32 s0, v249, 5
	v_readlane_b32 s1, v249, 6
	s_branch .LBB0_147

; DEV int opaque_tid() { int t = (int)threadIdx.x; asm volatile("" : "+v"(t)); return t; }
; __device__ void quant_rows_fp6(const float* __restrict__ src, unsigned char* __restrict__ dst, float* __restrict__ scl, int nrows) {
;   const int tid = opaque_tid(), lane = tid & 63, w = tid >> 6;
;   const int l32 = lane & 31, hf = lane >> 5;
;   for (int rp = blockIdx.x * 4 + w; rp < nrows / 2; rp += gridDim.x * 4) {
;     const int r = rp * 2 + hf;
;     const float4* p = (const float4*)(src + (size_t)r * 1024 + l32 * 32);
;     float v[32];
; #pragma unroll
;     for (int i = 0; i < 8; ++i) { const float4 t = p[i]; v[4 * i] = t.x; v[4 * i + 1] = t.y; v[4 * i + 2] = t.z; v[4 * i + 3] = t.w; }
; __device__ void run_phase(const Params& P, int ph, char* smem, bool do_store) {
;     ...
;       if (l == 0 && quant_first) { quant_rows_fp6(P.peer_u, P.U8, P.SU, 2 * 16384); quant_rows_fp4(P.peer_v, P.V8, P.SV, 2 * 16384); }
.LBB0_222:
	s_andn2_b64 vcc, exec, s[0:1]
	s_cbranch_vccnz .LBB0_309
	v_readlane_b32 s0, v249, 40
	s_cmp_lg_u32 s0, 1
	s_mov_b64 s[0:1], -1
	s_cbranch_scc0 .LBB0_283
	v_readlane_b32 s0, v248, 3
	v_readlane_b32 s1, v248, 4
	s_andn2_b64 vcc, exec, s[0:1]
	s_branch .LBB0_236
.Lq_entry:
	v_mov_b32_e32 v1, v202
	v_readlane_b32 s0, v251, 62
	v_ashrrev_i32_e32 v0, 6, v1
	s_nop 0
	v_add_u32_e32 v22, s0, v0
	v_cmp_gt_i32_e32 vcc, s97, v22
	s_and_saveexec_b64 s[0:1], vcc
	s_cbranch_execz .LBB0_230
	v_bfe_u32 v2, v1, 5, 1
	v_and_b32_e32 v1, 31, v1
	v_readlane_b32 s40, v252, 12
	v_lshlrev_b32_e32 v176, 7, v1
	v_readlane_b32 s41, v252, 13
	v_readlane_b32 s42, v252, 14
	v_readlane_b32 s43, v252, 15
	v_readlane_b32 s44, v252, 16
	v_readlane_b32 s45, v252, 17
	v_readlane_b32 s46, v252, 18
	v_readlane_b32 s47, v252, 19
	v_readlane_b32 s48, v252, 20
	v_readlane_b32 s49, v252, 21
	v_readlane_b32 s50, v252, 22
	v_readlane_b32 s51, v252, 23
	v_readlane_b32 s52, v252, 24
	v_readlane_b32 s53, v252, 25
	v_readlane_b32 s54, v252, 26
	v_readlane_b32 s55, v252, 27
	v_lshl_add_u64 v[16:17], s[46:47], 0, v[176:177]
	v_readlane_b32 s40, v251, 42
	v_and_b32_e32 v3, 64, v212
	v_readlane_b32 s41, v251, 43
	v_add_u32_e32 v3, 64, v3
	v_mul_u32_u24_e32 v176, 24, v1
	v_cmp_eq_u32_e64 s[40:41], 0, v1
	v_xor_b32_e32 v1, 1, v212
	v_cmp_lt_i32_e32 vcc, v1, v3
	v_readlane_b32 s4, v248, 34
	v_readlane_b32 s44, v251, 46
	v_cndmask_b32_e32 v1, v212, v1, vcc
	v_lshlrev_b32_e32 v23, 2, v1
	v_xor_b32_e32 v1, 2, v212
	v_cmp_lt_i32_e32 vcc, v1, v3
	v_readlane_b32 s45, v251, 47
	s_mov_b32 s6, s4
	v_cndmask_b32_e32 v1, v212, v1, vcc
	v_lshlrev_b32_e32 v24, 2, v1
	v_xor_b32_e32 v1, 4, v212
	v_cmp_lt_i32_e32 vcc, v1, v3
	s_lshl_b32 s2, s4, 1
	v_lshlrev_b32_e32 v0, 1, v0
	v_cndmask_b32_e32 v1, v212, v1, vcc
	v_lshlrev_b32_e32 v25, 2, v1
	v_xor_b32_e32 v1, 8, v212
	v_cmp_lt_i32_e32 vcc, v1, v3
	v_readlane_b32 s4, v249, 2
	v_lshl_add_u64 v[18:19], s[44:45], 0, v[176:177]
	v_cndmask_b32_e32 v1, v212, v1, vcc
	v_lshlrev_b32_e32 v26, 2, v1
	v_xor_b32_e32 v1, 16, v212
	v_cmp_lt_i32_e32 vcc, v1, v3
	v_add3_u32 v20, s4, v0, v2
	s_lshl_b32 s4, s6, 2
	v_cndmask_b32_e32 v1, v212, v1, vcc
	v_lshlrev_b32_e32 v27, 2, v1
	s_mov_b64 s[38:39], 0
	v_readlane_b32 s42, v251, 44
	v_readlane_b32 s43, v251, 45
	v_readlane_b32 s46, v251, 48
	v_readlane_b32 s47, v251, 49
	v_readlane_b32 s48, v251, 50
	v_readlane_b32 s49, v251, 51
	v_readlane_b32 s50, v251, 52
	v_readlane_b32 s51, v251, 53
	v_readlane_b32 s52, v251, 54
	v_readlane_b32 s53, v251, 55
	v_readlane_b32 s54, v251, 56
	v_readlane_b32 s55, v251, 57
	v_readlane_b32 s5, v248, 35
	v_ashrrev_i32_e32 v21, 31, v20
	v_lshlrev_b64 v[96:97], 12, v[20:21]
	v_lshl_add_u64 v[96:97], v[16:17], 0, v[96:97]
	global_load_dwordx4 v[64:67], v[96:97], off
	global_load_dwordx4 v[68:71], v[96:97], off offset:16
	global_load_dwordx4 v[72:75], v[96:97], off offset:32
	global_load_dwordx4 v[76:79], v[96:97], off offset:48
	global_load_dwordx4 v[80:83], v[96:97], off offset:64
	global_load_dwordx4 v[84:87], v[96:97], off offset:80
	global_load_dwordx4 v[88:91], v[96:97], off offset:96
	global_load_dwordx4 v[92:95], v[96:97], off offset:112
	s_waitcnt vmcnt(0)
	s_branch .Lq6a_copy

; DEV int opaque_tid() { int t = (int)threadIdx.x; asm volatile("" : "+v"(t)); return t; }
; __device__ void quant_rows_fp4(const float* __restrict__ src, unsigned char* __restrict__ dst, float* __restrict__ scl, int nrows) {
;   const int tid = opaque_tid(), lane = tid & 63, w = tid >> 6;
;   for (int r = blockIdx.x * 4 + w; r < nrows; r += gridDim.x * 4) {
;     const float4* p = (const float4*)(src + (size_t)r * 1024 + lane * 16);
;     const float4 a = p[0], b = p[1], c = p[2], d = p[3];
.LBB0_230:
	s_waitcnt vmcnt(0)
	s_or_b64 exec, exec, s[0:1]
	v_mov_b32_e32 v1, v202
	v_readlane_b32 s0, v251, 62
	v_ashrrev_i32_e32 v0, 6, v1
	s_nop 0
	v_add_u32_e32 v0, s0, v0
	s_mov_b32 s0, 0x8000
	v_cmp_gt_i32_e32 vcc, s0, v0
	s_and_saveexec_b64 s[0:1], vcc
	s_cbranch_execz .LBB0_235
	v_and_b32_e32 v1, 63, v1
	v_readlane_b32 s40, v252, 12
	v_lshlrev_b32_e32 v176, 6, v1
	v_readlane_b32 s41, v252, 13
	v_readlane_b32 s42, v252, 14
	v_readlane_b32 s43, v252, 15
	v_readlane_b32 s44, v252, 16
	v_readlane_b32 s45, v252, 17
	v_readlane_b32 s46, v252, 18
	v_readlane_b32 s47, v252, 19
	v_readlane_b32 s48, v252, 20
	v_readlane_b32 s49, v252, 21
	v_readlane_b32 s50, v252, 22
	v_readlane_b32 s51, v252, 23
	v_readlane_b32 s52, v252, 24
	v_readlane_b32 s53, v252, 25
	v_readlane_b32 s54, v252, 26
	v_readlane_b32 s55, v252, 27
	v_lshl_add_u64 v[2:3], s[48:49], 0, v[176:177]
	v_readlane_b32 s40, v251, 42
	v_and_b32_e32 v4, 64, v212
	v_readlane_b32 s41, v251, 43
	v_add_u32_e32 v11, 64, v4
	v_lshlrev_b32_e32 v176, 3, v1
	v_cmp_eq_u32_e64 s[40:41], 0, v1
	v_xor_b32_e32 v1, 1, v212
	v_cmp_lt_i32_e32 vcc, v1, v11
	v_readlane_b32 s46, v251, 48
	v_readlane_b32 s47, v251, 49
	v_cndmask_b32_e32 v1, v212, v1, vcc
	v_lshlrev_b32_e32 v6, 2, v1
	v_xor_b32_e32 v1, 2, v212
	v_cmp_lt_i32_e32 vcc, v1, v11
	v_readlane_b32 s4, v248, 34
	v_lshl_add_u64 v[4:5], s[46:47], 0, v[176:177]
	v_cndmask_b32_e32 v1, v212, v1, vcc
	v_lshlrev_b32_e32 v7, 2, v1
	v_xor_b32_e32 v1, 4, v212
	v_cmp_lt_i32_e32 vcc, v1, v11
	s_lshl_b32 s2, s4, 1
	s_mov_b64 s[38:39], 0
	v_cndmask_b32_e32 v1, v212, v1, vcc
	v_lshlrev_b32_e32 v8, 2, v1
	v_xor_b32_e32 v1, 8, v212
	v_cmp_lt_i32_e32 vcc, v1, v11
	v_readlane_b32 s42, v251, 44
	v_readlane_b32 s43, v251, 45
	v_cndmask_b32_e32 v1, v212, v1, vcc
	v_lshlrev_b32_e32 v9, 2, v1
	v_xor_b32_e32 v1, 16, v212
	v_cmp_lt_i32_e32 vcc, v1, v11
	v_readlane_b32 s44, v251, 46
	v_readlane_b32 s45, v251, 47
	v_cndmask_b32_e32 v1, v212, v1, vcc
	v_lshlrev_b32_e32 v10, 2, v1
	v_xor_b32_e32 v1, 32, v212
	v_cmp_lt_i32_e32 vcc, v1, v11
	v_readlane_b32 s48, v251, 50
	v_readlane_b32 s49, v251, 51
	v_cndmask_b32_e32 v1, v212, v1, vcc
	v_lshlrev_b32_e32 v11, 2, v1
	v_readlane_b32 s50, v251, 52
	v_readlane_b32 s51, v251, 53
	v_readlane_b32 s52, v251, 54
	v_readlane_b32 s53, v251, 55
	v_readlane_b32 s54, v251, 56
	v_readlane_b32 s55, v251, 57
	v_readlane_b32 s5, v248, 35
	v_ashrrev_i32_e32 v1, 31, v0
	v_lshlrev_b64 v[96:97], 12, v[0:1]
	v_lshl_add_u64 v[96:97], v[2:3], 0, v[96:97]
	global_load_dwordx4 v[64:67], v[96:97], off offset:48
	global_load_dwordx4 v[68:71], v[96:97], off offset:32
	global_load_dwordx4 v[72:75], v[96:97], off offset:16
	global_load_dwordx4 v[76:79], v[96:97], off
	s_waitcnt vmcnt(0)
	s_branch .Lq4a_copy

; __device__ void run_phase(const Params& P, int ph, char* smem, bool do_store) {
;     ...
;       if (l == 0 && quant_first) { quant_rows_fp6(P.peer_u, P.U8, P.SU, 2 * 16384); quant_rows_fp4(P.peer_v, P.V8, P.SV, 2 * 16384); }
;       gemm_phase256<0>(P, l, P.XB, P.WinT + (size_t)l * NINP * 1024, 19, smem);
;       if (l == 0 && !quant_first) { quant_rows_fp6(P.peer_u, P.U8, P.SU, 2 * 16384); quant_rows_fp4(P.peer_v, P.V8, P.SV, 2 * 16384); }
.LBB0_235:
	s_waitcnt vmcnt(0)
	s_or_b64 exec, exec, s[0:1]
	s_branch .Lnsa_resume

; __device__ void run_phase(const Params& P, int ph, char* smem, bool do_store) {
;     ...
;       if (l == 0 && !quant_first) { quant_rows_fp6(P.peer_u, P.U8, P.SU, 2 * 16384); quant_rows_fp4(P.peer_v, P.V8, P.SV, 2 * 16384); }
.LBB0_270:
	v_readlane_b32 s0, v248, 7
	v_readlane_b32 s1, v248, 8
	s_andn2_b64 vcc, exec, s[0:1]
	s_branch .LBB0_282
